# MLA: softmax row sums on the matrix core (ones(16x32) x P^T, 4 MFMA per 64-key tile) instead of 32 dependent v_add per tile; no cross-lane reduce at the end
# speedup vs baseline: 1.0082x; 1.0065x over previous
; template <bool MLA> __device__ __forceinline__ void attn_unit(const AttnP& P, int b, int hh, int qb, LAS char* lds) {
;     ...
;     const int qlo = q0 + wid * 32, qm = qlo + r32 - 4 * hi;
;     bf16x8 qr[NQF];
;     const size_t qrow = rowbase + qlo + r32;
;     if constexpr (MLA) {
; #pragma unroll
;         for (int d0 = 0; d0 < 8; ++d0) qr[d0] = *(const bf16x8*)(P.QN + qrow * 2048 + hh * 128 + d0 * 16 + hi * 8);
; #pragma unroll
;         for (int d0 = 0; d0 < 4; ++d0) qr[8 + d0] = *(const bf16x8*)(P.QR + qrow * 1024 + hh * 64 + d0 * 16 + hi * 8);
;     } else {
; #pragma unroll
;         for (int d0 = 0; d0 < 4; ++d0) qr[d0] = *(const bf16x8*)(P.QS + qrow * 2048 + hh * 64 + d0 * 16 + hi * 8);
;         if (tid < 128) bias_l[tid] = P.rel[(int)T5B[tid] * 32 + hh] * (1.0f / SCALE);
;     }
;     bf16x8 sk0, sv0;
;     const int sr8 = tid >> 3, ch8 = tid & 7;
;     const bf16_t* Kg; const bf16_t* Vg; const bf16_t* Rg = nullptr;
;     unsigned okA = 0, okB = 0, orp = 0, ovA = 0, ovB = 0;
;     if constexpr (MLA) {
;         Kg = P.KN + rowbase * 2048 + hh * 128; Vg = P.V + rowbase * 2048 + hh * 128; Rg = P.KR + rowbase * 64;
;         { const int rA = 4 * wid + (lane >> 4), rB = rA + 32, cp = lane & 15; okA = (unsigned)(rA * 2048 + ((cp ^ (rA & 7)) << 3)); okB = (unsigned)(rB * 2048 + ((cp ^ (rB & 7)) << 3)); }
;         { const int rr = 8 * wid + (lane >> 3), cp = lane & 7; orp = (unsigned)(rr * 64 + ((cp ^ (rr & 7)) << 3)); }
;         { const int stA = 2 * wid + (lane >> 5), stB = stA + 16; const int kl = (lane & 31) >> 2, c8 = 8 * (lane & 3);
;           const int kkA = (stA >> 2) * 8 + kl, kkB = (stB >> 2) * 8 + kl;
;           const int kA = (kkA & ~0xC) | ((kkA & 4) << 1) | ((kkA & 8) >> 1), kB = (kkB & ~0xC) | ((kkB & 4) << 1) | ((kkB & 8) >> 1);
;           ovA = (unsigned)(kA * 2048 + 32 * (stA & 3) + c8); ovB = (unsigned)(kB * 2048 + 32 * (stB & 3) + c8); }
;     } else { Kg = P.KS + (rowbase + sr8) * 256 + (hh >> 3) * 64 + ch8 * 8; Vg = P.VS + (rowbase + sr8) * 256 + (hh >> 3) * 64 + ch8 * 8; }
;     const int kws = KSWZ64(sr8, ch8), vst0 = v_st<NCB>(sr8, ch8 * 8);
;     ...
;     float m_reg = MLA ? 0.f : P.sinks[hh] * (1.0f / SCALE), l_reg = MLA ? 0.f : 1.f;
;     f32x16 o[NCB];
; #pragma unroll
;     for (int d = 0; d < NCB; ++d) o[d] = f32x16{};
;     const int vb0 = (int)(uintptr_t)V_lds + v_rd_base(lane);
.Lm16_qb_ok:
	s_lshr_b32 s36, s28, 5
	s_and_b32 s63, s36, 15
	s_lshr_b32 s64, s36, 4
	s_lshl_b32 s40, s33, 2
	s_add_u32 s40, s40, 4
	s_lshl_b32 s43, s33, 8
	s_lshl_b32 s36, s4, 5
	s_add_u32 s43, s43, s36
	s_lshl_b32 s36, s64, 14
	s_add_u32 s36, s36, s43
	s_lshl_b32 s37, s36, 12
	s_lshl_b32 s59, s63, 8
	s_add_u32 s37, s37, s59
	s_add_u32 s66, s6, s37
	s_addc_u32 s67, s7, 0
	s_lshl_b32 s37, s36, 11
	s_lshl_b32 s59, s63, 7
	s_add_u32 s37, s37, s59
	s_add_u32 s68, s8, s37
	s_addc_u32 s69, s9, 0
	s_lshl_b32 s37, s64, 26
	s_lshl_b32 s59, s63, 8
	s_add_u32 s37, s37, s59
	s_add_u32 s46, s12, s37
	s_addc_u32 s47, s13, 0
	s_add_u32 s48, s16, s37
	s_addc_u32 s49, s17, 0
	s_lshl_b32 s37, s64, 21
	s_add_u32 s50, s14, s37
	s_addc_u32 s51, s15, 0
	global_load_dwordx4 v[66:69], v237, s[66:67] offset:0
	global_load_dwordx4 v[70:73], v237, s[66:67] offset:64
	global_load_dwordx4 v[74:77], v237, s[66:67] offset:128
	global_load_dwordx4 v[78:81], v237, s[66:67] offset:192
	global_load_dwordx4 v[82:85], v239, s[68:69] offset:0
	global_load_dwordx4 v[86:89], v239, s[68:69] offset:64
	global_load_dwordx4 v[90:93], v238, s[66:67] offset:0
	global_load_dwordx4 v[94:97], v238, s[66:67] offset:64
	global_load_dwordx4 v[98:101], v238, s[66:67] offset:128
	global_load_dwordx4 v[102:105], v238, s[66:67] offset:192
	global_load_dwordx4 v[106:109], v240, s[68:69] offset:0
	global_load_dwordx4 v[110:113], v240, s[68:69] offset:64
	s_mov_b32 s70, 0x8000
	s_mov_b32 s71, 0
	s_add_i32 s36, s5, s70
	s_mov_b32 m0, s36
	s_nop 0
	global_load_lds_dwordx4 v232, s[46:47]
	s_add_i32 m0, s36, 0x2000
	s_nop 0
	global_load_lds_dwordx4 v233, s[46:47]
	s_add_i32 m0, s36, 0x4000
	s_nop 0
	global_load_lds_dwordx4 v234, s[50:51]
	s_add_i32 s36, s5, s71
	s_mov_b32 m0, s36
	s_nop 0
	global_load_lds_dwordx4 v235, s[48:49]
	s_add_i32 m0, s36, 0x2000
	s_nop 0
	global_load_lds_dwordx4 v236, s[48:49]
	s_add_u32 s46, s46, 0x40000
	s_addc_u32 s47, s47, 0
	s_add_u32 s48, s48, 0x40000
	s_addc_u32 s49, s49, 0
	s_add_u32 s50, s50, 0x2000
	s_addc_u32 s51, s51, 0
	v_mov_b32_e32 v2, 0
	v_mov_b32_e32 v3, 0
	v_mov_b32_e32 v4, 0
	v_mov_b32_e32 v5, 0
	v_mov_b32_e32 v6, 0
	v_mov_b32_e32 v7, 0
	v_mov_b32_e32 v8, 0
	v_mov_b32_e32 v9, 0
	v_mov_b32_e32 v10, 0
	v_mov_b32_e32 v11, 0
	v_mov_b32_e32 v12, 0
	v_mov_b32_e32 v13, 0
	v_mov_b32_e32 v14, 0
	v_mov_b32_e32 v15, 0
	v_mov_b32_e32 v16, 0
	v_mov_b32_e32 v17, 0
	v_mov_b32_e32 v18, 0
	v_mov_b32_e32 v19, 0
	v_mov_b32_e32 v20, 0
	v_mov_b32_e32 v21, 0
	v_mov_b32_e32 v22, 0
	v_mov_b32_e32 v23, 0
	v_mov_b32_e32 v24, 0
	v_mov_b32_e32 v25, 0
	v_mov_b32_e32 v26, 0
	v_mov_b32_e32 v27, 0
	v_mov_b32_e32 v28, 0
	v_mov_b32_e32 v29, 0
	v_mov_b32_e32 v30, 0
	v_mov_b32_e32 v31, 0
	v_mov_b32_e32 v32, 0
	v_mov_b32_e32 v33, 0
	v_mov_b32_e32 v34, 0
	v_mov_b32_e32 v35, 0
	v_mov_b32_e32 v36, 0
	v_mov_b32_e32 v37, 0
	v_mov_b32_e32 v38, 0
	v_mov_b32_e32 v39, 0
	v_mov_b32_e32 v40, 0
	v_mov_b32_e32 v41, 0
	v_mov_b32_e32 v42, 0
	v_mov_b32_e32 v43, 0
	v_mov_b32_e32 v44, 0
	v_mov_b32_e32 v45, 0
	v_mov_b32_e32 v46, 0
	v_mov_b32_e32 v47, 0
	v_mov_b32_e32 v48, 0
	v_mov_b32_e32 v49, 0
	v_mov_b32_e32 v50, 0
	v_mov_b32_e32 v51, 0
	v_mov_b32_e32 v52, 0
	v_mov_b32_e32 v53, 0
	v_mov_b32_e32 v54, 0
	v_mov_b32_e32 v55, 0
	v_mov_b32_e32 v56, 0
	v_mov_b32_e32 v57, 0
	v_mov_b32_e32 v58, 0
	v_mov_b32_e32 v59, 0
	v_mov_b32_e32 v60, 0
	v_mov_b32_e32 v61, 0
	v_mov_b32_e32 v62, 0
	v_mov_b32_e32 v63, 0
	v_mov_b32_e32 v64, 0
	v_mov_b32_e32 v65, 0
	v_mov_b32_e32 v218, 0
	v_mov_b32_e32 v146, 0
	v_mov_b32_e32 v154, 0x3f803f80
	v_mov_b32_e32 v147, 0
	v_mov_b32_e32 v155, 0x3f803f80
	v_mov_b32_e32 v148, 0
	v_mov_b32_e32 v156, 0x3f803f80
	v_mov_b32_e32 v149, 0
	v_mov_b32_e32 v157, 0x3f803f80
	v_mov_b32_e32 v208, 0
	v_mov_b32_e32 v209, 0
	v_mov_b32_e32 v210, 0
	v_mov_b32_e32 v211, 0
	v_mov_b32_e32 v219, 0
	v_mov_b32_e32 v150, 0
	v_mov_b32_e32 v154, 0x3f803f80
	v_mov_b32_e32 v151, 0
	v_mov_b32_e32 v155, 0x3f803f80
	v_mov_b32_e32 v152, 0
	v_mov_b32_e32 v156, 0x3f803f80
	v_mov_b32_e32 v153, 0
	v_mov_b32_e32 v157, 0x3f803f80
	v_mov_b32_e32 v212, 0
	v_mov_b32_e32 v213, 0
	v_mov_b32_e32 v214, 0
	v_mov_b32_e32 v215, 0
	s_mov_b32 s41, 0
	s_mov_b32 s42, 0
	s_waitcnt vmcnt(0)
	s_barrier

; __device__ __forceinline__ int crow(int r, int hi) { return (r & 3) + 8 * (r >> 2) + 4 * hi; }
; __device__ __forceinline__ void partialSM_pre(f32x16& p0, f32x16& p1, float& m_reg, float& alpha) {
;     constexpr float THR2 = THR * 1.4426950408889634f;
;     float pmax = p0[0];
; #pragma unroll
;     for (int r = 1; r < 16; ++r) pmax = fmaxf(pmax, p0[r]);
; #pragma unroll
;     for (int r = 0; r < 16; ++r) pmax = fmaxf(pmax, p1[r]);
;     { auto rr = __builtin_amdgcn_permlane32_swap(__float_as_uint(pmax), __float_as_uint(pmax), false, false);
;       pmax = fmaxf(__uint_as_float(rr[0]), __uint_as_float(rr[1])); }
;     if (__builtin_expect(__all(pmax <= THR2), 1)) { alpha = 1.f; }
;     else { const float d = fmaxf(pmax, 0.f); m_reg += d; alpha = __builtin_amdgcn_exp2f(-d);
; #pragma unroll
;         for (int r = 0; r < 16; ++r) { p0[r] -= d; p1[r] -= d; } }
; template <bool MLA> __device__ __forceinline__ void attn_unit(const AttnP& P, int b, int hh, int qb, LAS char* lds) {
;     ...
;             if (__any(alpha < 1.f)) { if (hi == 0) al_l[r32] = alpha; asm volatile("s_waitcnt lgkmcnt(0)" ::: "memory");
; #pragma unroll
;                 for (int d_ = 0; d_ < NCB; ++d_)
; #pragma unroll
;                     for (int r = 0; r < 16; ++r) o[d_][r] *= al_l[crow(r, hi)]; }
.Lm16_nomask:
	v_max3_f32 v220, v114, v115, v116
	v_max3_f32 v220, v220, v117, v118
	v_max3_f32 v220, v220, v119, v120
	v_max3_f32 v220, v220, v121, v122
	v_max3_f32 v220, v220, v123, v124
	v_max3_f32 v220, v220, v125, v126
	v_max3_f32 v220, v220, v127, v128
	v_max3_f32 v220, v220, v129, v130
	v_max3_f32 v220, v220, v131, v132
	v_max3_f32 v220, v220, v133, v134
	v_max3_f32 v220, v220, v135, v136
	v_max3_f32 v220, v220, v137, v138
	v_max3_f32 v220, v220, v139, v140
	v_max3_f32 v220, v220, v141, v142
	v_max3_f32 v220, v220, v143, v144
	v_max_f32_e32 v220, v220, v145
	v_cmp_ge_f32_e32 vcc, s72, v220
	s_cmp_eq_u64 vcc, exec
	s_cbranch_scc1 .Lm16_exp
	v_max3_f32 v220, v114, v115, v116
	v_max3_f32 v220, v220, v117, v122
	v_max3_f32 v220, v220, v123, v124
	v_max3_f32 v220, v220, v125, v130
	v_max3_f32 v220, v220, v131, v132
	v_max3_f32 v220, v220, v133, v138
	v_max3_f32 v220, v220, v139, v140
	v_max_f32_e32 v220, v220, v141
	ds_bpermute_b32 v221, v246, v220
	s_waitcnt lgkmcnt(0)
	v_max_f32_e32 v220, v220, v221
	ds_bpermute_b32 v221, v247, v220
	s_waitcnt lgkmcnt(0)
	v_max_f32_e32 v220, v220, v221
	v_max_f32_e32 v221, 0, v220
	v_add_f32_e32 v218, v218, v221
	v_exp_f32_e64 v222, -v221
	v_sub_f32_e32 v114, v114, v221
	v_sub_f32_e32 v115, v115, v221
	v_sub_f32_e32 v116, v116, v221
	v_sub_f32_e32 v117, v117, v221
	v_sub_f32_e32 v122, v122, v221
	v_sub_f32_e32 v123, v123, v221
	v_sub_f32_e32 v124, v124, v221
	v_sub_f32_e32 v125, v125, v221
	v_sub_f32_e32 v130, v130, v221
	v_sub_f32_e32 v131, v131, v221
	v_sub_f32_e32 v132, v132, v221
	v_sub_f32_e32 v133, v133, v221
	v_sub_f32_e32 v138, v138, v221
	v_sub_f32_e32 v139, v139, v221
	v_sub_f32_e32 v140, v140, v221
	v_sub_f32_e32 v141, v141, v221
	v_mul_f32_e32 v146, v146, v222
	v_mul_f32_e32 v147, v147, v222
	v_mul_f32_e32 v148, v148, v222
	v_mul_f32_e32 v149, v149, v222
	v_mul_f32_e32 v2, v2, v222
	v_mul_f32_e32 v3, v3, v222
	v_mul_f32_e32 v4, v4, v222
	v_mul_f32_e32 v5, v5, v222
	v_mul_f32_e32 v10, v10, v222
	v_mul_f32_e32 v11, v11, v222
	v_mul_f32_e32 v12, v12, v222
	v_mul_f32_e32 v13, v13, v222
	v_mul_f32_e32 v18, v18, v222
	v_mul_f32_e32 v19, v19, v222
	v_mul_f32_e32 v20, v20, v222
	v_mul_f32_e32 v21, v21, v222
	v_mul_f32_e32 v26, v26, v222
	v_mul_f32_e32 v27, v27, v222
	v_mul_f32_e32 v28, v28, v222
	v_mul_f32_e32 v29, v29, v222
	v_mul_f32_e32 v34, v34, v222
	v_mul_f32_e32 v35, v35, v222
	v_mul_f32_e32 v36, v36, v222
	v_mul_f32_e32 v37, v37, v222
	v_mul_f32_e32 v42, v42, v222
	v_mul_f32_e32 v43, v43, v222
	v_mul_f32_e32 v44, v44, v222
	v_mul_f32_e32 v45, v45, v222
	v_mul_f32_e32 v50, v50, v222
	v_mul_f32_e32 v51, v51, v222
	v_mul_f32_e32 v52, v52, v222
	v_mul_f32_e32 v53, v53, v222
	v_mul_f32_e32 v58, v58, v222
	v_mul_f32_e32 v59, v59, v222
	v_mul_f32_e32 v60, v60, v222
	v_mul_f32_e32 v61, v61, v222
	v_xor_b32_e32 v208, 0x80000000, v218
	v_xor_b32_e32 v209, 0x80000000, v218
	v_xor_b32_e32 v210, 0x80000000, v218
	v_xor_b32_e32 v211, 0x80000000, v218
	v_max3_f32 v220, v118, v119, v120
	v_max3_f32 v220, v220, v121, v126
	v_max3_f32 v220, v220, v127, v128
	v_max3_f32 v220, v220, v129, v134
	v_max3_f32 v220, v220, v135, v136
	v_max3_f32 v220, v220, v137, v142
	v_max3_f32 v220, v220, v143, v144
	v_max_f32_e32 v220, v220, v145
	ds_bpermute_b32 v221, v246, v220
	s_waitcnt lgkmcnt(0)
	v_max_f32_e32 v220, v220, v221
	ds_bpermute_b32 v221, v247, v220
	s_waitcnt lgkmcnt(0)
	v_max_f32_e32 v220, v220, v221
	v_max_f32_e32 v221, 0, v220
	v_add_f32_e32 v219, v219, v221
	v_exp_f32_e64 v222, -v221
	v_sub_f32_e32 v118, v118, v221
	v_sub_f32_e32 v119, v119, v221
	v_sub_f32_e32 v120, v120, v221
	v_sub_f32_e32 v121, v121, v221
	v_sub_f32_e32 v126, v126, v221
	v_sub_f32_e32 v127, v127, v221
	v_sub_f32_e32 v128, v128, v221
	v_sub_f32_e32 v129, v129, v221
	v_sub_f32_e32 v134, v134, v221
	v_sub_f32_e32 v135, v135, v221
	v_sub_f32_e32 v136, v136, v221
	v_sub_f32_e32 v137, v137, v221
	v_sub_f32_e32 v142, v142, v221
	v_sub_f32_e32 v143, v143, v221
	v_sub_f32_e32 v144, v144, v221
	v_sub_f32_e32 v145, v145, v221
	v_mul_f32_e32 v150, v150, v222
	v_mul_f32_e32 v151, v151, v222
	v_mul_f32_e32 v152, v152, v222
	v_mul_f32_e32 v153, v153, v222
	v_mul_f32_e32 v6, v6, v222
	v_mul_f32_e32 v7, v7, v222
	v_mul_f32_e32 v8, v8, v222
	v_mul_f32_e32 v9, v9, v222
	v_mul_f32_e32 v14, v14, v222
	v_mul_f32_e32 v15, v15, v222
	v_mul_f32_e32 v16, v16, v222
	v_mul_f32_e32 v17, v17, v222
	v_mul_f32_e32 v22, v22, v222
	v_mul_f32_e32 v23, v23, v222
	v_mul_f32_e32 v24, v24, v222
	v_mul_f32_e32 v25, v25, v222
	v_mul_f32_e32 v30, v30, v222
	v_mul_f32_e32 v31, v31, v222
	v_mul_f32_e32 v32, v32, v222
	v_mul_f32_e32 v33, v33, v222
	v_mul_f32_e32 v38, v38, v222
	v_mul_f32_e32 v39, v39, v222
	v_mul_f32_e32 v40, v40, v222
	v_mul_f32_e32 v41, v41, v222
	v_mul_f32_e32 v46, v46, v222
	v_mul_f32_e32 v47, v47, v222
	v_mul_f32_e32 v48, v48, v222
	v_mul_f32_e32 v49, v49, v222
	v_mul_f32_e32 v54, v54, v222
	v_mul_f32_e32 v55, v55, v222
	v_mul_f32_e32 v56, v56, v222
	v_mul_f32_e32 v57, v57, v222
	v_mul_f32_e32 v62, v62, v222
	v_mul_f32_e32 v63, v63, v222
	v_mul_f32_e32 v64, v64, v222
	v_mul_f32_e32 v65, v65, v222
	v_xor_b32_e32 v212, 0x80000000, v219
	v_xor_b32_e32 v213, 0x80000000, v219
	v_xor_b32_e32 v214, 0x80000000, v219
	v_xor_b32_e32 v215, 0x80000000, v219
; #define PV_RD(S, d0) do { constexpr int b_ = (d0) * 512; TRRD(S##l0, b_); TRRD(S##h0, b_ + KS_ / 2); TRRD(S##l1, b_ + KS_); TRRD(S##h1, b_ + KS_ + KS_ / 2); TRRD(S##l2, b_ + 2 * KS_); TRRD(S##h2, b_ + 2 * KS_ + KS_ / 2); TRRD(S##l3, b_ + 3 * KS_); TRRD(S##h3, b_ + 3 * KS_ + KS_ / 2); } while (0)
; #define WL(n) do { asm volatile("s_waitcnt lgkmcnt(" #n ")" ::: "memory"); SBAR(); } while (0)
; __device__ __forceinline__ void finishSM(f32x16& p0, f32x16& p1, float alpha, float& l_reg, bf16x8& pa0, bf16x8& pa1, bf16x8& pa2, bf16x8& pa3) {
; #pragma unroll
;     for (int r = 0; r < 16; ++r) p1[r] = __builtin_amdgcn_exp2f(p1[r]);
;     float ps = 0;
; #pragma unroll
;     for (int r = 0; r < 16; ++r) ps += p0[r];
; #pragma unroll
;     for (int r = 0; r < 16; ++r) ps += p1[r];
;     { auto rr = __builtin_amdgcn_permlane32_swap(__float_as_uint(ps), __float_as_uint(ps), false, false);
;       ps = __uint_as_float(rr[0]) + __uint_as_float(rr[1]); }
;     l_reg = l_reg * alpha + ps;
;     ...
;     PK4(p0, 0, pa0); PK4(p0, 8, pa1); PK4(p1, 0, pa2); PK4(p1, 8, pa3);
; template <int NCB> __device__ __forceinline__ void pv_tile(f32x16* o, int vb, bf16x8 pa0, bf16x8 pa1, bf16x8 pa2, bf16x8 pa3) {
;     ...
;     constexpr int KS_ = NCB * 1024;
;     ...
;     s16x4 Al0, Al1, Al2, Al3, Ah0, Ah1, Ah2, Ah3, Bl0, Bl1, Bl2, Bl3, Bh0, Bh1, Bh2, Bh3;
;     PV_RD(A, 0); PV_RD(B, 1); WL(8); PV_MM(A, 0);
;     if constexpr (NCB == 4) { PV_RD(A, 2); WL(8); PV_MM(B, 1); PV_RD(B, 3); WL(8); PV_MM(A, 2); WL(0); PV_MM(B, 3); }
;     else { WL(0); PV_MM(B, 1); }
.Lm16_exp:
	v_exp_f32_e32 v114, v114
	v_exp_f32_e32 v115, v115
	v_exp_f32_e32 v116, v116
	v_exp_f32_e32 v117, v117
	v_exp_f32_e32 v118, v118
	v_exp_f32_e32 v119, v119
	v_exp_f32_e32 v120, v120
	v_exp_f32_e32 v121, v121
	v_exp_f32_e32 v122, v122
	v_exp_f32_e32 v123, v123
	v_exp_f32_e32 v124, v124
	v_exp_f32_e32 v125, v125
	v_exp_f32_e32 v126, v126
	v_exp_f32_e32 v127, v127
	v_exp_f32_e32 v128, v128
	v_exp_f32_e32 v129, v129
	v_exp_f32_e32 v130, v130
	v_exp_f32_e32 v131, v131
	v_exp_f32_e32 v132, v132
	v_exp_f32_e32 v133, v133
	v_exp_f32_e32 v134, v134
	v_exp_f32_e32 v135, v135
	v_exp_f32_e32 v136, v136
	v_exp_f32_e32 v137, v137
	v_exp_f32_e32 v138, v138
	v_exp_f32_e32 v139, v139
	v_exp_f32_e32 v140, v140
	v_exp_f32_e32 v141, v141
	v_exp_f32_e32 v142, v142
	v_exp_f32_e32 v143, v143
	v_exp_f32_e32 v144, v144
	v_exp_f32_e32 v145, v145
	v_cvt_pk_bf16_f32 v164, v114, v115
	v_cvt_pk_bf16_f32 v165, v116, v117
	v_cvt_pk_bf16_f32 v166, v122, v123
	v_cvt_pk_bf16_f32 v167, v124, v125
	v_cvt_pk_bf16_f32 v168, v130, v131
	v_cvt_pk_bf16_f32 v169, v132, v133
	v_cvt_pk_bf16_f32 v170, v138, v139
	v_cvt_pk_bf16_f32 v171, v140, v141
	v_cvt_pk_bf16_f32 v172, v118, v119
	v_cvt_pk_bf16_f32 v173, v120, v121
	v_cvt_pk_bf16_f32 v174, v126, v127
	v_cvt_pk_bf16_f32 v175, v128, v129
	v_cvt_pk_bf16_f32 v176, v134, v135
	v_cvt_pk_bf16_f32 v177, v136, v137
	v_cvt_pk_bf16_f32 v178, v142, v143
	v_cvt_pk_bf16_f32 v179, v144, v145
	ds_read_b64_tr_b16 v[180:181], v230 offset:0
	ds_read_b64_tr_b16 v[182:183], v230 offset:4096
	ds_read_b64_tr_b16 v[184:185], v230 offset:8192
	ds_read_b64_tr_b16 v[186:187], v230 offset:12288
	ds_read_b64_tr_b16 v[188:189], v231 offset:0
	ds_read_b64_tr_b16 v[190:191], v231 offset:4096
	ds_read_b64_tr_b16 v[192:193], v231 offset:8192
	ds_read_b64_tr_b16 v[194:195], v231 offset:12288
	s_waitcnt lgkmcnt(6)
	v_mfma_f32_16x16x32_bf16 v[2:5], v[180:183], v[164:167], v[2:5]
	v_mfma_f32_16x16x32_bf16 v[6:9], v[180:183], v[172:175], v[6:9]
	v_mfma_f32_16x16x32_bf16 v[146:149], v[154:157], v[164:167], v[146:149]
	v_mfma_f32_16x16x32_bf16 v[150:153], v[154:157], v[172:175], v[150:153]
	ds_read_b64_tr_b16 v[180:181], v230 offset:512
	ds_read_b64_tr_b16 v[182:183], v230 offset:4608
	s_waitcnt lgkmcnt(6)
	v_mfma_f32_16x16x32_bf16 v[2:5], v[184:187], v[168:171], v[2:5]
	v_mfma_f32_16x16x32_bf16 v[6:9], v[184:187], v[176:179], v[6:9]
	v_mfma_f32_16x16x32_bf16 v[146:149], v[154:157], v[168:171], v[146:149]
	v_mfma_f32_16x16x32_bf16 v[150:153], v[154:157], v[176:179], v[150:153]
	ds_read_b64_tr_b16 v[184:185], v230 offset:8704
	ds_read_b64_tr_b16 v[186:187], v230 offset:12800
	s_waitcnt lgkmcnt(6)
	v_mfma_f32_16x16x32_bf16 v[10:13], v[188:191], v[164:167], v[10:13]
	v_mfma_f32_16x16x32_bf16 v[14:17], v[188:191], v[172:175], v[14:17]
	ds_read_b64_tr_b16 v[188:189], v231 offset:512
	ds_read_b64_tr_b16 v[190:191], v231 offset:4608
	s_waitcnt lgkmcnt(6)
	v_mfma_f32_16x16x32_bf16 v[10:13], v[192:195], v[168:171], v[10:13]
	v_mfma_f32_16x16x32_bf16 v[14:17], v[192:195], v[176:179], v[14:17]
	ds_read_b64_tr_b16 v[192:193], v231 offset:8704
	ds_read_b64_tr_b16 v[194:195], v231 offset:12800
	s_waitcnt lgkmcnt(6)
	v_mfma_f32_16x16x32_bf16 v[18:21], v[180:183], v[164:167], v[18:21]
	v_mfma_f32_16x16x32_bf16 v[22:25], v[180:183], v[172:175], v[22:25]
	ds_read_b64_tr_b16 v[180:181], v230 offset:1024
	ds_read_b64_tr_b16 v[182:183], v230 offset:5120
	s_waitcnt lgkmcnt(6)
	v_mfma_f32_16x16x32_bf16 v[18:21], v[184:187], v[168:171], v[18:21]
	v_mfma_f32_16x16x32_bf16 v[22:25], v[184:187], v[176:179], v[22:25]
	ds_read_b64_tr_b16 v[184:185], v230 offset:9216
	ds_read_b64_tr_b16 v[186:187], v230 offset:13312
	s_waitcnt lgkmcnt(6)
	v_mfma_f32_16x16x32_bf16 v[26:29], v[188:191], v[164:167], v[26:29]
	v_mfma_f32_16x16x32_bf16 v[30:33], v[188:191], v[172:175], v[30:33]
	ds_read_b64_tr_b16 v[188:189], v231 offset:1024
	ds_read_b64_tr_b16 v[190:191], v231 offset:5120
	s_waitcnt lgkmcnt(6)
	v_mfma_f32_16x16x32_bf16 v[26:29], v[192:195], v[168:171], v[26:29]
	v_mfma_f32_16x16x32_bf16 v[30:33], v[192:195], v[176:179], v[30:33]
	ds_read_b64_tr_b16 v[192:193], v231 offset:9216
	ds_read_b64_tr_b16 v[194:195], v231 offset:13312
	s_waitcnt lgkmcnt(6)
	v_mfma_f32_16x16x32_bf16 v[34:37], v[180:183], v[164:167], v[34:37]
	v_mfma_f32_16x16x32_bf16 v[38:41], v[180:183], v[172:175], v[38:41]
	ds_read_b64_tr_b16 v[180:181], v230 offset:1536
	ds_read_b64_tr_b16 v[182:183], v230 offset:5632
	s_waitcnt lgkmcnt(6)
	v_mfma_f32_16x16x32_bf16 v[34:37], v[184:187], v[168:171], v[34:37]
	v_mfma_f32_16x16x32_bf16 v[38:41], v[184:187], v[176:179], v[38:41]
	ds_read_b64_tr_b16 v[184:185], v230 offset:9728
	ds_read_b64_tr_b16 v[186:187], v230 offset:13824
	s_waitcnt lgkmcnt(6)
	v_mfma_f32_16x16x32_bf16 v[42:45], v[188:191], v[164:167], v[42:45]
	v_mfma_f32_16x16x32_bf16 v[46:49], v[188:191], v[172:175], v[46:49]
	ds_read_b64_tr_b16 v[188:189], v231 offset:1536
	ds_read_b64_tr_b16 v[190:191], v231 offset:5632
	s_waitcnt lgkmcnt(6)
	v_mfma_f32_16x16x32_bf16 v[42:45], v[192:195], v[168:171], v[42:45]
	v_mfma_f32_16x16x32_bf16 v[46:49], v[192:195], v[176:179], v[46:49]
	ds_read_b64_tr_b16 v[192:193], v231 offset:9728
	ds_read_b64_tr_b16 v[194:195], v231 offset:13824
	s_waitcnt lgkmcnt(6)
	v_mfma_f32_16x16x32_bf16 v[50:53], v[180:183], v[164:167], v[50:53]
	v_mfma_f32_16x16x32_bf16 v[54:57], v[180:183], v[172:175], v[54:57]
	s_waitcnt lgkmcnt(4)
	v_mfma_f32_16x16x32_bf16 v[50:53], v[184:187], v[168:171], v[50:53]
	v_mfma_f32_16x16x32_bf16 v[54:57], v[184:187], v[176:179], v[54:57]
	s_waitcnt lgkmcnt(2)
	v_mfma_f32_16x16x32_bf16 v[58:61], v[188:191], v[164:167], v[58:61]
	v_mfma_f32_16x16x32_bf16 v[62:65], v[188:191], v[172:175], v[62:65]
	s_waitcnt lgkmcnt(0)
	v_mfma_f32_16x16x32_bf16 v[58:61], v[192:195], v[168:171], v[58:61]
	v_mfma_f32_16x16x32_bf16 v[62:65], v[192:195], v[176:179], v[62:65]
; #define LAS __attribute__((address_space(3)))
; __device__ __forceinline__ int crow(int r, int hi) { return (r & 3) + 8 * (r >> 2) + 4 * hi; }
; __device__ __forceinline__ unsigned cvtpk(float lo, float hi) { f32x2_cv v = {lo, hi}; bf16x2_cv b = __builtin_convertvector(v, bf16x2_cv); return __builtin_bit_cast(unsigned, b); }
; template <bool MLA> __device__ __forceinline__ void attn_unit(const AttnP& P, int b, int hh, int qb, LAS char* lds) {
;     ...
;         __syncthreads();
;     }
;     if (hi == 0) li_l[r32] = l_reg; asm volatile("s_waitcnt lgkmcnt(0)" ::: "memory");
;     bf16_t* Ow = (MLA ? P.QN + (rowbase + qlo) * 2048 + hh * 128 : P.QS + (rowbase + qlo) * 2048 + hh * 64);
; #pragma unroll
;     for (int r = 0; r < 16; ++r) { const int orow = crow(r, hi); const float rl = __builtin_amdgcn_rcpf(li_l[orow]);
; #pragma unroll
;         for (int d0 = 0; d0 < NCB; ++d0) { const float v = o[d0][r] * rl; const float vn = __shfl_xor(v, 1);
;             if ((r32 & 1) == 0) *(unsigned*)(Ow + (size_t)orow * 2048 + d0 * 32 + r32) = cvtpk(v, vn); } }
; __global__ void __launch_bounds__(512) fwd_mega(Args a) {
;     ...
;         for (int it = vcu; it < 1024; it += G) { const int bh = it >> 5, s = it & 31;
;             att::attn_unit<true>(P, bh >> 4, bh & 15, 63 - s, (LAS char*)lds);
;             att::attn_unit<true>(P, bh >> 4, bh & 15, s, (LAS char*)lds); }
.Lm16_tile_end:
	s_waitcnt vmcnt(0) lgkmcnt(0)
	s_barrier
	s_add_u32 s41, s41, 1
	s_add_u32 s42, s42, 64
	s_cmp_lt_u32 s41, s40
	s_cbranch_scc1 .Lm16_tile
	s_nop 7
	v_rcp_f32_e32 v216, v146
	v_rcp_f32_e32 v217, v150
	s_nop 0
	v_mul_f32_e32 v2, v2, v216
	v_mul_f32_e32 v3, v3, v216
	v_mul_f32_e32 v4, v4, v216
	v_mul_f32_e32 v5, v5, v216
	v_cvt_pk_bf16_f32 v2, v2, v3
	v_cvt_pk_bf16_f32 v3, v4, v5
	global_store_dwordx2 v241, v[2:3], s[66:67] offset:0
	v_mul_f32_e32 v6, v6, v217
	v_mul_f32_e32 v7, v7, v217
	v_mul_f32_e32 v8, v8, v217
	v_mul_f32_e32 v9, v9, v217
	v_cvt_pk_bf16_f32 v6, v6, v7
	v_cvt_pk_bf16_f32 v7, v8, v9
	global_store_dwordx2 v242, v[6:7], s[66:67] offset:0
	v_mul_f32_e32 v10, v10, v216
	v_mul_f32_e32 v11, v11, v216
	v_mul_f32_e32 v12, v12, v216
	v_mul_f32_e32 v13, v13, v216
	v_cvt_pk_bf16_f32 v10, v10, v11
	v_cvt_pk_bf16_f32 v11, v12, v13
	global_store_dwordx2 v241, v[10:11], s[66:67] offset:32
	v_mul_f32_e32 v14, v14, v217
	v_mul_f32_e32 v15, v15, v217
	v_mul_f32_e32 v16, v16, v217
	v_mul_f32_e32 v17, v17, v217
	v_cvt_pk_bf16_f32 v14, v14, v15
	v_cvt_pk_bf16_f32 v15, v16, v17
	global_store_dwordx2 v242, v[14:15], s[66:67] offset:32
	v_mul_f32_e32 v18, v18, v216
	v_mul_f32_e32 v19, v19, v216
	v_mul_f32_e32 v20, v20, v216
	v_mul_f32_e32 v21, v21, v216
	v_cvt_pk_bf16_f32 v18, v18, v19
	v_cvt_pk_bf16_f32 v19, v20, v21
	global_store_dwordx2 v241, v[18:19], s[66:67] offset:64
	v_mul_f32_e32 v22, v22, v217
	v_mul_f32_e32 v23, v23, v217
	v_mul_f32_e32 v24, v24, v217
	v_mul_f32_e32 v25, v25, v217
	v_cvt_pk_bf16_f32 v22, v22, v23
	v_cvt_pk_bf16_f32 v23, v24, v25
	global_store_dwordx2 v242, v[22:23], s[66:67] offset:64
	v_mul_f32_e32 v26, v26, v216
	v_mul_f32_e32 v27, v27, v216
	v_mul_f32_e32 v28, v28, v216
	v_mul_f32_e32 v29, v29, v216
	v_cvt_pk_bf16_f32 v26, v26, v27
	v_cvt_pk_bf16_f32 v27, v28, v29
	global_store_dwordx2 v241, v[26:27], s[66:67] offset:96
	v_mul_f32_e32 v30, v30, v217
	v_mul_f32_e32 v31, v31, v217
	v_mul_f32_e32 v32, v32, v217
	v_mul_f32_e32 v33, v33, v217
	v_cvt_pk_bf16_f32 v30, v30, v31
	v_cvt_pk_bf16_f32 v31, v32, v33
	global_store_dwordx2 v242, v[30:31], s[66:67] offset:96
	v_mul_f32_e32 v34, v34, v216
	v_mul_f32_e32 v35, v35, v216
	v_mul_f32_e32 v36, v36, v216
	v_mul_f32_e32 v37, v37, v216
	v_cvt_pk_bf16_f32 v34, v34, v35
	v_cvt_pk_bf16_f32 v35, v36, v37
	global_store_dwordx2 v241, v[34:35], s[66:67] offset:128
	v_mul_f32_e32 v38, v38, v217
	v_mul_f32_e32 v39, v39, v217
	v_mul_f32_e32 v40, v40, v217
	v_mul_f32_e32 v41, v41, v217
	v_cvt_pk_bf16_f32 v38, v38, v39
	v_cvt_pk_bf16_f32 v39, v40, v41
	global_store_dwordx2 v242, v[38:39], s[66:67] offset:128
	v_mul_f32_e32 v42, v42, v216
	v_mul_f32_e32 v43, v43, v216
	v_mul_f32_e32 v44, v44, v216
	v_mul_f32_e32 v45, v45, v216
	v_cvt_pk_bf16_f32 v42, v42, v43
	v_cvt_pk_bf16_f32 v43, v44, v45
	global_store_dwordx2 v241, v[42:43], s[66:67] offset:160
	v_mul_f32_e32 v46, v46, v217
	v_mul_f32_e32 v47, v47, v217
	v_mul_f32_e32 v48, v48, v217
	v_mul_f32_e32 v49, v49, v217
	v_cvt_pk_bf16_f32 v46, v46, v47
	v_cvt_pk_bf16_f32 v47, v48, v49
	global_store_dwordx2 v242, v[46:47], s[66:67] offset:160
	v_mul_f32_e32 v50, v50, v216
	v_mul_f32_e32 v51, v51, v216
	v_mul_f32_e32 v52, v52, v216
	v_mul_f32_e32 v53, v53, v216
	v_cvt_pk_bf16_f32 v50, v50, v51
	v_cvt_pk_bf16_f32 v51, v52, v53
	global_store_dwordx2 v241, v[50:51], s[66:67] offset:192
	v_mul_f32_e32 v54, v54, v217
	v_mul_f32_e32 v55, v55, v217
	v_mul_f32_e32 v56, v56, v217
	v_mul_f32_e32 v57, v57, v217
	v_cvt_pk_bf16_f32 v54, v54, v55
	v_cvt_pk_bf16_f32 v55, v56, v57
	global_store_dwordx2 v242, v[54:55], s[66:67] offset:192
	v_mul_f32_e32 v58, v58, v216
	v_mul_f32_e32 v59, v59, v216
	v_mul_f32_e32 v60, v60, v216
	v_mul_f32_e32 v61, v61, v216
	v_cvt_pk_bf16_f32 v58, v58, v59
	v_cvt_pk_bf16_f32 v59, v60, v61
	global_store_dwordx2 v241, v[58:59], s[66:67] offset:224
	v_mul_f32_e32 v62, v62, v217
	v_mul_f32_e32 v63, v63, v217
	v_mul_f32_e32 v64, v64, v217
	v_mul_f32_e32 v65, v65, v217
	v_cvt_pk_bf16_f32 v62, v62, v63
	v_cvt_pk_bf16_f32 v63, v64, v65
	global_store_dwordx2 v242, v[62:63], s[66:67] offset:224
	s_add_u32 s29, s29, 1
	s_cmp_lt_u32 s29, 2
	s_cbranch_scc1 .Lm16_unit
	s_add_u32 s28, s28, s3
	s_cmp_lt_u32 s28, 0x400
	s_cbranch_scc1 .Lm16_item
	s_waitcnt vmcnt(0) lgkmcnt(0)
